# phase 9 KV epilogue: the 8 per-row rstd loads issued together at the head, counted vmcnt so stores are not drained per group
# speedup vs baseline: 1.0023x; 1.0023x over previous
; __device__ __forceinline__ unsigned cvt_pk_bf16(float lo, float hi) { unsigned r; asm volatile("v_cvt_pk_bf16_f32 %0, %1, %2" : "=v"(r) : "v"(lo), "v"(hi)); return r; }
; __device__ __forceinline__ u32x4 pack8(const f32x4 a, const f32x4 b) { u32x4 w; w.x = cvt_pk_bf16(a[0], a[1]); w.y = cvt_pk_bf16(a[2], a[3]); w.z = cvt_pk_bf16(b[0], b[1]); w.w = cvt_pk_bf16(b[2], b[3]); return w; }
;     __device__ __forceinline__ void operator()(const f32x4 (&acc)[2][2][4][2], const pg8::Unit& u, int wr, int wc, int fr, int fq) const {
;         const int row0 = u.pm * 256 + wr * 64 + fr, cw = wc * 32 + 8 * fq;
;         const int b = u.pm >> 4, s0 = (u.pm & 15) * 256 + wr * 64 + fr;
; #pragma unroll
;         for (int ai = 0; ai < 2; ++ai)
; #pragma unroll
;             for (int m = 0; m < 4; ++m) {
;                 const int row = row0 + ai * 128 + m * 16, s = s0 + ai * 128 + m * 16;
;                 const float rs = 1.0f / sqrtf(SS[(size_t)row * 2 + 1] * (1.0f / 512.0f) + 1e-6f);
;                 *(u32x4*)(KN + (size_t)row * 2048 + u.pn * 128 + cw) = pack8(acc[ai][0][m][0] * rs, acc[ai][0][m][1] * rs);
;                 bf16_t* vp = VtM + (size_t)((b * 16 + u.pn) * 128 + cw) * SEQ + s;
; #pragma unroll
;                 for (int n = 0; n < 2; ++n) {
;                     const f32x4 x = acc[ai][1][m][n] * rs;
;                     const unsigned p0 = cvt_pk_bf16(x[0], x[1]), p1 = cvt_pk_bf16(x[2], x[3]);
;                     vp[(size_t)(4 * n + 0) * SEQ] = (bf16_t)(p0 & 0xffffu); vp[(size_t)(4 * n + 1) * SEQ] = (bf16_t)(p0 >> 16);
;                     vp[(size_t)(4 * n + 2) * SEQ] = (bf16_t)(p1 & 0xffffu); vp[(size_t)(4 * n + 3) * SEQ] = (bf16_t)(p1 >> 16);
;                 }
;                 asm volatile("" ::: "memory");
.LBB0_1059:
	s_lshl_b32 s9, s26, 8
	v_add_u32_e32 v162, s9, v139
	v_ashrrev_i32_e32 v163, 31, v162
	v_lshl_add_u64 v[148:149], v[162:163], 3, s[16:17]
	global_load_dword v160, v[148:149], off offset:4
	global_load_dword v246, v[148:149], off offset:132
	global_load_dword v247, v[148:149], off offset:260
	global_load_dword v248, v[148:149], off offset:388
	global_load_dword v249, v[148:149], off offset:1028
	global_load_dword v250, v[148:149], off offset:1156
	global_load_dword v251, v[148:149], off offset:1284
	global_load_dword v252, v[148:149], off offset:1412
	s_and_b32 s26, s26, 0x1fffff0
	s_add_i32 s26, s26, s27
	s_lshl_b32 s8, s27, 7
	v_lshl_or_b32 v150, s26, 7, v138
	s_and_b32 s48, s9, 0xf00
	s_ashr_i32 s9, s8, 31
	v_ashrrev_i32_e32 v151, 31, v150
	v_lshlrev_b64 v[152:153], 12, v[162:163]
	v_add_u32_e32 v148, s48, v139
	s_lshl_b64 s[48:49], s[8:9], 1
	v_lshlrev_b64 v[150:151], 13, v[150:151]
	v_lshl_add_u64 v[152:153], s[38:39], 0, v[152:153]
	v_lshlrev_b32_e32 v136, 1, v138
	v_ashrrev_i32_e32 v149, 31, v148
	v_lshl_add_u64 v[152:153], v[152:153], 0, s[48:49]
	v_lshl_add_u64 v[150:151], s[18:19], 0, v[150:151]
	v_lshl_add_u64 v[190:191], v[152:153], 0, v[136:137]
	v_lshl_add_u64 v[152:153], v[148:149], 1, v[150:151]
	v_add_co_u32_e32 v154, vcc, s61, v152
	v_or_b32_e32 v186, 16, v162
	s_nop 0
	v_addc_co_u32_e32 v155, vcc, 0, v153, vcc
	v_add_co_u32_e32 v156, vcc, s62, v152
	v_ashrrev_i32_e32 v187, 31, v186
	s_nop 0
	v_addc_co_u32_e32 v157, vcc, 0, v153, vcc
	v_add_co_u32_e32 v158, vcc, s63, v152
	v_lshl_add_u64 v[188:189], v[186:187], 3, s[16:17]
	s_nop 0
	v_addc_co_u32_e32 v159, vcc, 0, v153, vcc
	v_add_co_u32_e32 v148, vcc, s71, v152
	s_waitcnt vmcnt(7)
	v_fmamk_f32 v160, v160, 0x3b000000, v183
	v_addc_co_u32_e32 v149, vcc, 0, v153, vcc
	v_add_co_u32_e32 v150, vcc, s73, v152
	v_mul_f32_e32 v161, 0x4f800000, v160
	s_nop 0
	v_addc_co_u32_e32 v151, vcc, 0, v153, vcc
	v_cmp_gt_f32_e32 vcc, s83, v160
	s_nop 1
	v_cndmask_b32_e32 v163, v160, v161, vcc
	v_sqrt_f32_e32 v164, v163
	v_add_co_u32_e64 v160, s[8:9], s79, v152
	v_add_u32_e32 v165, -1, v164
	s_nop 0
	v_addc_co_u32_e64 v161, s[8:9], 0, v153, s[8:9]
	v_add_u32_e32 v185, 1, v164
	v_fma_f32 v192, -v165, v164, v163
	v_fma_f32 v193, -v185, v164, v163
	v_cmp_ge_f32_e64 s[8:9], 0, v192
	s_nop 1
	v_cndmask_b32_e64 v164, v164, v165, s[8:9]
	v_cmp_lt_f32_e64 s[8:9], 0, v193
	s_nop 1
	v_cndmask_b32_e64 v164, v164, v185, s[8:9]
	v_mul_f32_e32 v165, 0x37800000, v164
	v_cndmask_b32_e32 v164, v164, v165, vcc
	v_cmp_class_f32_e32 vcc, v163, v184
	s_nop 1
	v_cndmask_b32_e32 v163, v164, v163, vcc
	v_div_scale_f32 v185, s[8:9], v163, v163, 1.0
	v_rcp_f32_e32 v192, v185
	v_add_co_u32_e32 v164, vcc, s81, v152
	v_fma_f32 v194, -v185, v192, 1.0
	s_nop 0
	v_addc_co_u32_e32 v165, vcc, 0, v153, vcc
	v_div_scale_f32 v193, vcc, 1.0, v163, 1.0
	v_fmac_f32_e32 v192, v194, v192
	v_mul_f32_e32 v194, v193, v192
	v_fma_f32 v195, -v185, v194, v193
	v_fmac_f32_e32 v194, v195, v192
	v_fma_f32 v185, -v185, v194, v193
	v_div_fmas_f32 v185, v185, v192, v194
	v_div_fixup_f32 v192, v185, v163, 1.0
	v_pk_mul_f32 v[126:127], v[126:127], v[192:193] op_sel_hi:[1,0]
	v_pk_mul_f32 v[124:125], v[124:125], v[192:193] op_sel_hi:[1,0]
	v_pk_mul_f32 v[122:123], v[122:123], v[192:193] op_sel_hi:[1,0]
	v_pk_mul_f32 v[120:121], v[120:121], v[192:193] op_sel_hi:[1,0]
	v_pk_mul_f32 v[118:119], v[118:119], v[192:193] op_sel_hi:[1,0]
	v_pk_mul_f32 v[116:117], v[116:117], v[192:193] op_sel_hi:[1,0]
	v_pk_mul_f32 v[194:195], v[114:115], v[192:193] op_sel_hi:[1,0]
	v_pk_mul_f32 v[192:193], v[112:113], v[192:193] op_sel_hi:[1,0]
	v_cvt_pk_bf16_f32 v112, v124, v125
	v_cvt_pk_bf16_f32 v113, v126, v127
	v_cvt_pk_bf16_f32 v114, v120, v121
	v_cvt_pk_bf16_f32 v115, v122, v123
	global_store_dwordx4 v[190:191], v[112:115], off
	s_nop 1
	v_cvt_pk_bf16_f32 v112, v116, v117
	v_cvt_pk_bf16_f32 v113, v118, v119
	global_store_short v[152:153], v112, off
	global_store_short_d16_hi v[154:155], v112, off
	global_store_short v[156:157], v113, off
	global_store_short_d16_hi v[158:159], v113, off
	v_cvt_pk_bf16_f32 v112, v192, v193
	v_cvt_pk_bf16_f32 v113, v194, v195
	global_store_short v[148:149], v112, off
	global_store_short_d16_hi v[150:151], v112, off
	global_store_short v[160:161], v113, off
	global_store_short_d16_hi v[164:165], v113, off
	s_waitcnt vmcnt(15)
; __device__ __forceinline__ unsigned cvt_pk_bf16(float lo, float hi) { unsigned r; asm volatile("v_cvt_pk_bf16_f32 %0, %1, %2" : "=v"(r) : "v"(lo), "v"(hi)); return r; }
; __device__ __forceinline__ u32x4 pack8(const f32x4 a, const f32x4 b) { u32x4 w; w.x = cvt_pk_bf16(a[0], a[1]); w.y = cvt_pk_bf16(a[2], a[3]); w.z = cvt_pk_bf16(b[0], b[1]); w.w = cvt_pk_bf16(b[2], b[3]); return w; }
;     __device__ __forceinline__ void operator()(const f32x4 (&acc)[2][2][4][2], const pg8::Unit& u, int wr, int wc, int fr, int fq) const {
;     ...
;                 const int row = row0 + ai * 128 + m * 16, s = s0 + ai * 128 + m * 16;
;                 const float rs = 1.0f / sqrtf(SS[(size_t)row * 2 + 1] * (1.0f / 512.0f) + 1e-6f);
;                 *(u32x4*)(KN + (size_t)row * 2048 + u.pn * 128 + cw) = pack8(acc[ai][0][m][0] * rs, acc[ai][0][m][1] * rs);
;                 bf16_t* vp = VtM + (size_t)((b * 16 + u.pn) * 128 + cw) * SEQ + s;
; #pragma unroll
;                 for (int n = 0; n < 2; ++n) {
;                     const f32x4 x = acc[ai][1][m][n] * rs;
;                     const unsigned p0 = cvt_pk_bf16(x[0], x[1]), p1 = cvt_pk_bf16(x[2], x[3]);
;                     vp[(size_t)(4 * n + 0) * SEQ] = (bf16_t)(p0 & 0xffffu); vp[(size_t)(4 * n + 1) * SEQ] = (bf16_t)(p0 >> 16);
;                     vp[(size_t)(4 * n + 2) * SEQ] = (bf16_t)(p1 & 0xffffu); vp[(size_t)(4 * n + 3) * SEQ] = (bf16_t)(p1 >> 16);
;                 }
	v_mov_b32_e32 v116, v246
	v_lshlrev_b64 v[114:115], 12, v[186:187]
	v_lshl_add_u64 v[114:115], s[38:39], 0, v[114:115]
	v_lshl_add_u64 v[114:115], v[114:115], 0, s[48:49]
	v_lshl_add_u64 v[114:115], v[114:115], 0, v[136:137]
	v_or_b32_e32 v112, 32, v162
	v_ashrrev_i32_e32 v113, 31, v112
	v_fmamk_f32 v116, v116, 0x3b000000, v183
	v_mul_f32_e32 v117, 0x4f800000, v116
	v_cmp_gt_f32_e32 vcc, s83, v116
	s_nop 1
	v_cndmask_b32_e32 v118, v116, v117, vcc
	v_sqrt_f32_e32 v119, v118
	v_lshl_add_u64 v[116:117], v[112:113], 3, s[16:17]
	v_add_u32_e32 v120, -1, v119
	v_add_u32_e32 v121, 1, v119
	v_fma_f32 v122, -v120, v119, v118
	v_fma_f32 v123, -v121, v119, v118
	v_cmp_ge_f32_e64 s[8:9], 0, v122
	s_nop 1
	v_cndmask_b32_e64 v119, v119, v120, s[8:9]
	v_cmp_lt_f32_e64 s[8:9], 0, v123
	s_nop 1
	v_cndmask_b32_e64 v119, v119, v121, s[8:9]
	v_mul_f32_e32 v120, 0x37800000, v119
	v_cndmask_b32_e32 v119, v119, v120, vcc
	v_cmp_class_f32_e32 vcc, v118, v184
	s_nop 1
	v_cndmask_b32_e32 v118, v119, v118, vcc
	v_div_scale_f32 v119, s[8:9], v118, v118, 1.0
	v_rcp_f32_e32 v120, v119
	v_div_scale_f32 v121, vcc, 1.0, v118, 1.0
	v_fma_f32 v122, -v119, v120, 1.0
	v_fmac_f32_e32 v120, v122, v120
	v_mul_f32_e32 v122, v121, v120
	v_fma_f32 v123, -v119, v122, v121
	v_fmac_f32_e32 v122, v123, v120
	v_fma_f32 v119, -v119, v122, v121
	v_div_fmas_f32 v119, v119, v120, v122
	v_div_fixup_f32 v118, v119, v118, 1.0
	v_pk_mul_f32 v[110:111], v[110:111], v[118:119] op_sel_hi:[1,0]
	v_pk_mul_f32 v[108:109], v[108:109], v[118:119] op_sel_hi:[1,0]
	v_pk_mul_f32 v[106:107], v[106:107], v[118:119] op_sel_hi:[1,0]
	v_pk_mul_f32 v[104:105], v[104:105], v[118:119] op_sel_hi:[1,0]
	v_pk_mul_f32 v[102:103], v[102:103], v[118:119] op_sel_hi:[1,0]
	v_pk_mul_f32 v[100:101], v[100:101], v[118:119] op_sel_hi:[1,0]
	v_pk_mul_f32 v[120:121], v[98:99], v[118:119] op_sel_hi:[1,0]
	v_pk_mul_f32 v[118:119], v[96:97], v[118:119] op_sel_hi:[1,0]
	v_cvt_pk_bf16_f32 v96, v108, v109
	v_cvt_pk_bf16_f32 v97, v110, v111
	v_cvt_pk_bf16_f32 v98, v104, v105
	v_cvt_pk_bf16_f32 v99, v106, v107
	global_store_dwordx4 v[114:115], v[96:99], off
	s_nop 1
	v_cvt_pk_bf16_f32 v96, v100, v101
	v_cvt_pk_bf16_f32 v97, v102, v103
	global_store_short v[152:153], v96, off offset:32
	global_store_short_d16_hi v[154:155], v96, off offset:32
	global_store_short v[156:157], v97, off offset:32
	global_store_short_d16_hi v[158:159], v97, off offset:32
	v_cvt_pk_bf16_f32 v96, v118, v119
	v_cvt_pk_bf16_f32 v97, v120, v121
	global_store_short v[148:149], v96, off offset:32
	global_store_short_d16_hi v[150:151], v96, off offset:32
	global_store_short v[160:161], v97, off offset:32
	global_store_short_d16_hi v[164:165], v97, off offset:32
	s_waitcnt vmcnt(23)
	v_mov_b32_e32 v100, v247
	v_lshlrev_b64 v[98:99], 12, v[112:113]
	v_lshl_add_u64 v[98:99], s[38:39], 0, v[98:99]
	v_lshl_add_u64 v[98:99], v[98:99], 0, s[48:49]
	v_lshl_add_u64 v[98:99], v[98:99], 0, v[136:137]
	v_or_b32_e32 v96, 48, v162
	v_ashrrev_i32_e32 v97, 31, v96
	v_fmamk_f32 v100, v100, 0x3b000000, v183
	v_mul_f32_e32 v101, 0x4f800000, v100
	v_cmp_gt_f32_e32 vcc, s83, v100
	s_nop 1
	v_cndmask_b32_e32 v102, v100, v101, vcc
	v_sqrt_f32_e32 v103, v102
	v_lshl_add_u64 v[100:101], v[96:97], 3, s[16:17]
	v_add_u32_e32 v104, -1, v103
	v_add_u32_e32 v105, 1, v103
	v_fma_f32 v106, -v104, v103, v102
	v_fma_f32 v107, -v105, v103, v102
	v_cmp_ge_f32_e64 s[8:9], 0, v106
	s_nop 1
	v_cndmask_b32_e64 v103, v103, v104, s[8:9]
	v_cmp_lt_f32_e64 s[8:9], 0, v107
	s_nop 1
	v_cndmask_b32_e64 v103, v103, v105, s[8:9]
	v_mul_f32_e32 v104, 0x37800000, v103
	v_cndmask_b32_e32 v103, v103, v104, vcc
	v_cmp_class_f32_e32 vcc, v102, v184
	s_nop 1
	v_cndmask_b32_e32 v102, v103, v102, vcc
	v_div_scale_f32 v103, s[8:9], v102, v102, 1.0
	v_rcp_f32_e32 v104, v103
	v_div_scale_f32 v105, vcc, 1.0, v102, 1.0
	v_fma_f32 v106, -v103, v104, 1.0
	v_fmac_f32_e32 v104, v106, v104
	v_mul_f32_e32 v106, v105, v104
	v_fma_f32 v107, -v103, v106, v105
	v_fmac_f32_e32 v106, v107, v104
	v_fma_f32 v103, -v103, v106, v105
	v_div_fmas_f32 v103, v103, v104, v106
	v_div_fixup_f32 v102, v103, v102, 1.0
	v_pk_mul_f32 v[94:95], v[94:95], v[102:103] op_sel_hi:[1,0]
	v_pk_mul_f32 v[92:93], v[92:93], v[102:103] op_sel_hi:[1,0]
	v_pk_mul_f32 v[90:91], v[90:91], v[102:103] op_sel_hi:[1,0]
	v_pk_mul_f32 v[88:89], v[88:89], v[102:103] op_sel_hi:[1,0]
	v_pk_mul_f32 v[86:87], v[86:87], v[102:103] op_sel_hi:[1,0]
	v_pk_mul_f32 v[84:85], v[84:85], v[102:103] op_sel_hi:[1,0]
	v_pk_mul_f32 v[104:105], v[82:83], v[102:103] op_sel_hi:[1,0]
	v_pk_mul_f32 v[102:103], v[80:81], v[102:103] op_sel_hi:[1,0]
	v_cvt_pk_bf16_f32 v80, v92, v93
	v_cvt_pk_bf16_f32 v81, v94, v95
	v_cvt_pk_bf16_f32 v82, v88, v89
	v_cvt_pk_bf16_f32 v83, v90, v91
	global_store_dwordx4 v[98:99], v[80:83], off
	s_nop 1
	v_cvt_pk_bf16_f32 v80, v84, v85
	v_cvt_pk_bf16_f32 v81, v86, v87
	global_store_short v[152:153], v80, off offset:64
	global_store_short_d16_hi v[154:155], v80, off offset:64
	global_store_short v[156:157], v81, off offset:64
	global_store_short_d16_hi v[158:159], v81, off offset:64
	v_cvt_pk_bf16_f32 v80, v102, v103
	v_cvt_pk_bf16_f32 v81, v104, v105
	global_store_short v[148:149], v80, off offset:64
	global_store_short_d16_hi v[150:151], v80, off offset:64
	global_store_short v[160:161], v81, off offset:64
	global_store_short_d16_hi v[164:165], v81, off offset:64
	s_waitcnt vmcnt(31)
; __device__ __forceinline__ unsigned cvt_pk_bf16(float lo, float hi) { unsigned r; asm volatile("v_cvt_pk_bf16_f32 %0, %1, %2" : "=v"(r) : "v"(lo), "v"(hi)); return r; }
; __device__ __forceinline__ u32x4 pack8(const f32x4 a, const f32x4 b) { u32x4 w; w.x = cvt_pk_bf16(a[0], a[1]); w.y = cvt_pk_bf16(a[2], a[3]); w.z = cvt_pk_bf16(b[0], b[1]); w.w = cvt_pk_bf16(b[2], b[3]); return w; }
;     __device__ __forceinline__ void operator()(const f32x4 (&acc)[2][2][4][2], const pg8::Unit& u, int wr, int wc, int fr, int fq) const {
;     ...
;                 const int row = row0 + ai * 128 + m * 16, s = s0 + ai * 128 + m * 16;
;                 const float rs = 1.0f / sqrtf(SS[(size_t)row * 2 + 1] * (1.0f / 512.0f) + 1e-6f);
;                 *(u32x4*)(KN + (size_t)row * 2048 + u.pn * 128 + cw) = pack8(acc[ai][0][m][0] * rs, acc[ai][0][m][1] * rs);
;                 bf16_t* vp = VtM + (size_t)((b * 16 + u.pn) * 128 + cw) * SEQ + s;
; #pragma unroll
;                 for (int n = 0; n < 2; ++n) {
;                     const f32x4 x = acc[ai][1][m][n] * rs;
;                     const unsigned p0 = cvt_pk_bf16(x[0], x[1]), p1 = cvt_pk_bf16(x[2], x[3]);
;                     vp[(size_t)(4 * n + 0) * SEQ] = (bf16_t)(p0 & 0xffffu); vp[(size_t)(4 * n + 1) * SEQ] = (bf16_t)(p0 >> 16);
;                     vp[(size_t)(4 * n + 2) * SEQ] = (bf16_t)(p1 & 0xffffu); vp[(size_t)(4 * n + 3) * SEQ] = (bf16_t)(p1 >> 16);
;                 }
	v_mov_b32_e32 v84, v248
	v_lshlrev_b64 v[82:83], 12, v[96:97]
	v_lshl_add_u64 v[82:83], s[38:39], 0, v[82:83]
	v_lshl_add_u64 v[82:83], v[82:83], 0, s[48:49]
	v_lshl_add_u64 v[82:83], v[82:83], 0, v[136:137]
	v_add_u32_e32 v80, 0x80, v162
	v_ashrrev_i32_e32 v81, 31, v80
	v_fmamk_f32 v84, v84, 0x3b000000, v183
	v_mul_f32_e32 v85, 0x4f800000, v84
	v_cmp_gt_f32_e32 vcc, s83, v84
	s_nop 1
	v_cndmask_b32_e32 v86, v84, v85, vcc
	v_sqrt_f32_e32 v87, v86
	v_lshl_add_u64 v[84:85], v[80:81], 3, s[16:17]
	v_add_u32_e32 v88, -1, v87
	v_add_u32_e32 v89, 1, v87
	v_fma_f32 v90, -v88, v87, v86
	v_fma_f32 v91, -v89, v87, v86
	v_cmp_ge_f32_e64 s[8:9], 0, v90
	s_nop 1
	v_cndmask_b32_e64 v87, v87, v88, s[8:9]
	v_cmp_lt_f32_e64 s[8:9], 0, v91
	s_nop 1
	v_cndmask_b32_e64 v87, v87, v89, s[8:9]
	v_mul_f32_e32 v88, 0x37800000, v87
	v_cndmask_b32_e32 v87, v87, v88, vcc
	v_cmp_class_f32_e32 vcc, v86, v184
	s_nop 1
	v_cndmask_b32_e32 v86, v87, v86, vcc
	v_div_scale_f32 v87, s[8:9], v86, v86, 1.0
	v_rcp_f32_e32 v88, v87
	v_div_scale_f32 v89, vcc, 1.0, v86, 1.0
	v_fma_f32 v90, -v87, v88, 1.0
	v_fmac_f32_e32 v88, v90, v88
	v_mul_f32_e32 v90, v89, v88
	v_fma_f32 v91, -v87, v90, v89
	v_fmac_f32_e32 v90, v91, v88
	v_fma_f32 v87, -v87, v90, v89
	v_div_fmas_f32 v87, v87, v88, v90
	v_div_fixup_f32 v86, v87, v86, 1.0
	v_pk_mul_f32 v[78:79], v[78:79], v[86:87] op_sel_hi:[1,0]
	v_pk_mul_f32 v[76:77], v[76:77], v[86:87] op_sel_hi:[1,0]
	v_pk_mul_f32 v[74:75], v[74:75], v[86:87] op_sel_hi:[1,0]
	v_pk_mul_f32 v[72:73], v[72:73], v[86:87] op_sel_hi:[1,0]
	v_pk_mul_f32 v[70:71], v[70:71], v[86:87] op_sel_hi:[1,0]
	v_pk_mul_f32 v[68:69], v[68:69], v[86:87] op_sel_hi:[1,0]
	v_pk_mul_f32 v[88:89], v[66:67], v[86:87] op_sel_hi:[1,0]
	v_pk_mul_f32 v[86:87], v[64:65], v[86:87] op_sel_hi:[1,0]
	v_cvt_pk_bf16_f32 v64, v76, v77
	v_cvt_pk_bf16_f32 v65, v78, v79
	v_cvt_pk_bf16_f32 v66, v72, v73
	v_cvt_pk_bf16_f32 v67, v74, v75
	global_store_dwordx4 v[82:83], v[64:67], off
	s_nop 1
	v_cvt_pk_bf16_f32 v64, v68, v69
	v_cvt_pk_bf16_f32 v65, v70, v71
	global_store_short v[152:153], v64, off offset:96
	global_store_short_d16_hi v[154:155], v64, off offset:96
	global_store_short v[156:157], v65, off offset:96
	global_store_short_d16_hi v[158:159], v65, off offset:96
	v_cvt_pk_bf16_f32 v64, v86, v87
	v_cvt_pk_bf16_f32 v65, v88, v89
	global_store_short v[148:149], v64, off offset:96
	global_store_short_d16_hi v[150:151], v64, off offset:96
	global_store_short v[160:161], v65, off offset:96
	global_store_short_d16_hi v[164:165], v65, off offset:96
	s_waitcnt vmcnt(39)
	v_mov_b32_e32 v68, v249
	v_lshlrev_b64 v[66:67], 12, v[80:81]
	v_lshl_add_u64 v[66:67], s[38:39], 0, v[66:67]
	v_lshl_add_u64 v[66:67], v[66:67], 0, s[48:49]
	v_lshl_add_u64 v[66:67], v[66:67], 0, v[136:137]
	v_add_u32_e32 v64, 0x90, v162
	v_ashrrev_i32_e32 v65, 31, v64
	v_fmamk_f32 v68, v68, 0x3b000000, v183
	v_mul_f32_e32 v69, 0x4f800000, v68
	v_cmp_gt_f32_e32 vcc, s83, v68
	s_nop 1
	v_cndmask_b32_e32 v70, v68, v69, vcc
	v_sqrt_f32_e32 v71, v70
	v_lshl_add_u64 v[68:69], v[64:65], 3, s[16:17]
	v_add_u32_e32 v72, -1, v71
	v_add_u32_e32 v73, 1, v71
	v_fma_f32 v74, -v72, v71, v70
	v_fma_f32 v75, -v73, v71, v70
	v_cmp_ge_f32_e64 s[8:9], 0, v74
	s_nop 1
	v_cndmask_b32_e64 v71, v71, v72, s[8:9]
	v_cmp_lt_f32_e64 s[8:9], 0, v75
	s_nop 1
	v_cndmask_b32_e64 v71, v71, v73, s[8:9]
	v_mul_f32_e32 v72, 0x37800000, v71
	v_cndmask_b32_e32 v71, v71, v72, vcc
	v_cmp_class_f32_e32 vcc, v70, v184
	s_nop 1
	v_cndmask_b32_e32 v70, v71, v70, vcc
	v_div_scale_f32 v71, s[8:9], v70, v70, 1.0
	v_rcp_f32_e32 v72, v71
	v_div_scale_f32 v73, vcc, 1.0, v70, 1.0
	v_fma_f32 v74, -v71, v72, 1.0
	v_fmac_f32_e32 v72, v74, v72
	v_mul_f32_e32 v74, v73, v72
	v_fma_f32 v75, -v71, v74, v73
	v_fmac_f32_e32 v74, v75, v72
	v_fma_f32 v71, -v71, v74, v73
	v_div_fmas_f32 v71, v71, v72, v74
	v_div_fixup_f32 v70, v71, v70, 1.0
	v_pk_mul_f32 v[62:63], v[62:63], v[70:71] op_sel_hi:[1,0]
	v_pk_mul_f32 v[60:61], v[60:61], v[70:71] op_sel_hi:[1,0]
	v_pk_mul_f32 v[58:59], v[58:59], v[70:71] op_sel_hi:[1,0]
	v_pk_mul_f32 v[56:57], v[56:57], v[70:71] op_sel_hi:[1,0]
	v_pk_mul_f32 v[54:55], v[54:55], v[70:71] op_sel_hi:[1,0]
	v_pk_mul_f32 v[52:53], v[52:53], v[70:71] op_sel_hi:[1,0]
	v_pk_mul_f32 v[72:73], v[50:51], v[70:71] op_sel_hi:[1,0]
	v_pk_mul_f32 v[70:71], v[48:49], v[70:71] op_sel_hi:[1,0]
	v_cvt_pk_bf16_f32 v48, v60, v61
	v_cvt_pk_bf16_f32 v49, v62, v63
	v_cvt_pk_bf16_f32 v50, v56, v57
	v_cvt_pk_bf16_f32 v51, v58, v59
	global_store_dwordx4 v[66:67], v[48:51], off
	s_nop 1
	v_cvt_pk_bf16_f32 v48, v52, v53
	v_cvt_pk_bf16_f32 v49, v54, v55
	global_store_short v[152:153], v48, off offset:256
	global_store_short_d16_hi v[154:155], v48, off offset:256
	global_store_short v[156:157], v49, off offset:256
	global_store_short_d16_hi v[158:159], v49, off offset:256
	v_cvt_pk_bf16_f32 v48, v70, v71
	v_cvt_pk_bf16_f32 v49, v72, v73
	global_store_short v[148:149], v48, off offset:256
	global_store_short_d16_hi v[150:151], v48, off offset:256
	global_store_short v[160:161], v49, off offset:256
	global_store_short_d16_hi v[164:165], v49, off offset:256
	s_waitcnt vmcnt(47)
; __device__ __forceinline__ unsigned cvt_pk_bf16(float lo, float hi) { unsigned r; asm volatile("v_cvt_pk_bf16_f32 %0, %1, %2" : "=v"(r) : "v"(lo), "v"(hi)); return r; }
; __device__ __forceinline__ u32x4 pack8(const f32x4 a, const f32x4 b) { u32x4 w; w.x = cvt_pk_bf16(a[0], a[1]); w.y = cvt_pk_bf16(a[2], a[3]); w.z = cvt_pk_bf16(b[0], b[1]); w.w = cvt_pk_bf16(b[2], b[3]); return w; }
;     __device__ __forceinline__ void operator()(const f32x4 (&acc)[2][2][4][2], const pg8::Unit& u, int wr, int wc, int fr, int fq) const {
;     ...
;                 const int row = row0 + ai * 128 + m * 16, s = s0 + ai * 128 + m * 16;
;                 const float rs = 1.0f / sqrtf(SS[(size_t)row * 2 + 1] * (1.0f / 512.0f) + 1e-6f);
;                 *(u32x4*)(KN + (size_t)row * 2048 + u.pn * 128 + cw) = pack8(acc[ai][0][m][0] * rs, acc[ai][0][m][1] * rs);
;                 bf16_t* vp = VtM + (size_t)((b * 16 + u.pn) * 128 + cw) * SEQ + s;
; #pragma unroll
;                 for (int n = 0; n < 2; ++n) {
;                     const f32x4 x = acc[ai][1][m][n] * rs;
;                     const unsigned p0 = cvt_pk_bf16(x[0], x[1]), p1 = cvt_pk_bf16(x[2], x[3]);
;                     vp[(size_t)(4 * n + 0) * SEQ] = (bf16_t)(p0 & 0xffffu); vp[(size_t)(4 * n + 1) * SEQ] = (bf16_t)(p0 >> 16);
;                     vp[(size_t)(4 * n + 2) * SEQ] = (bf16_t)(p1 & 0xffffu); vp[(size_t)(4 * n + 3) * SEQ] = (bf16_t)(p1 >> 16);
;                 }
	v_mov_b32_e32 v52, v250
	v_lshlrev_b64 v[50:51], 12, v[64:65]
	v_lshl_add_u64 v[50:51], s[38:39], 0, v[50:51]
	v_lshl_add_u64 v[50:51], v[50:51], 0, s[48:49]
	v_lshl_add_u64 v[50:51], v[50:51], 0, v[136:137]
	v_add_u32_e32 v48, 0xa0, v162
	v_ashrrev_i32_e32 v49, 31, v48
	v_fmamk_f32 v52, v52, 0x3b000000, v183
	v_mul_f32_e32 v53, 0x4f800000, v52
	v_cmp_gt_f32_e32 vcc, s83, v52
	s_nop 1
	v_cndmask_b32_e32 v54, v52, v53, vcc
	v_sqrt_f32_e32 v55, v54
	v_lshl_add_u64 v[52:53], v[48:49], 3, s[16:17]
	v_add_u32_e32 v56, -1, v55
	v_add_u32_e32 v57, 1, v55
	v_fma_f32 v58, -v56, v55, v54
	v_fma_f32 v59, -v57, v55, v54
	v_cmp_ge_f32_e64 s[8:9], 0, v58
	s_nop 1
	v_cndmask_b32_e64 v55, v55, v56, s[8:9]
	v_cmp_lt_f32_e64 s[8:9], 0, v59
	s_nop 1
	v_cndmask_b32_e64 v55, v55, v57, s[8:9]
	v_mul_f32_e32 v56, 0x37800000, v55
	v_cndmask_b32_e32 v55, v55, v56, vcc
	v_cmp_class_f32_e32 vcc, v54, v184
	s_nop 1
	v_cndmask_b32_e32 v54, v55, v54, vcc
	v_div_scale_f32 v55, s[8:9], v54, v54, 1.0
	v_rcp_f32_e32 v56, v55
	v_div_scale_f32 v57, vcc, 1.0, v54, 1.0
	v_fma_f32 v58, -v55, v56, 1.0
	v_fmac_f32_e32 v56, v58, v56
	v_mul_f32_e32 v58, v57, v56
	v_fma_f32 v59, -v55, v58, v57
	v_fmac_f32_e32 v58, v59, v56
	v_fma_f32 v55, -v55, v58, v57
	v_div_fmas_f32 v55, v55, v56, v58
	v_div_fixup_f32 v54, v55, v54, 1.0
	v_pk_mul_f32 v[46:47], v[46:47], v[54:55] op_sel_hi:[1,0]
	v_pk_mul_f32 v[44:45], v[44:45], v[54:55] op_sel_hi:[1,0]
	v_pk_mul_f32 v[42:43], v[42:43], v[54:55] op_sel_hi:[1,0]
	v_pk_mul_f32 v[40:41], v[40:41], v[54:55] op_sel_hi:[1,0]
	v_pk_mul_f32 v[38:39], v[38:39], v[54:55] op_sel_hi:[1,0]
	v_pk_mul_f32 v[36:37], v[36:37], v[54:55] op_sel_hi:[1,0]
	v_pk_mul_f32 v[56:57], v[34:35], v[54:55] op_sel_hi:[1,0]
	v_pk_mul_f32 v[54:55], v[32:33], v[54:55] op_sel_hi:[1,0]
	v_cvt_pk_bf16_f32 v32, v44, v45
	v_cvt_pk_bf16_f32 v33, v46, v47
	v_cvt_pk_bf16_f32 v34, v40, v41
	v_cvt_pk_bf16_f32 v35, v42, v43
	global_store_dwordx4 v[50:51], v[32:35], off
	s_nop 1
	v_cvt_pk_bf16_f32 v32, v36, v37
	v_cvt_pk_bf16_f32 v33, v38, v39
	global_store_short v[152:153], v32, off offset:288
	global_store_short_d16_hi v[154:155], v32, off offset:288
	global_store_short v[156:157], v33, off offset:288
	global_store_short_d16_hi v[158:159], v33, off offset:288
	v_cvt_pk_bf16_f32 v32, v54, v55
	v_cvt_pk_bf16_f32 v33, v56, v57
	global_store_short v[148:149], v32, off offset:288
	global_store_short_d16_hi v[150:151], v32, off offset:288
	global_store_short v[160:161], v33, off offset:288
	global_store_short_d16_hi v[164:165], v33, off offset:288
	s_waitcnt vmcnt(55)
; __device__ __forceinline__ unsigned cvt_pk_bf16(float lo, float hi) { unsigned r; asm volatile("v_cvt_pk_bf16_f32 %0, %1, %2" : "=v"(r) : "v"(lo), "v"(hi)); return r; }
; __device__ __forceinline__ u32x4 pack8(const f32x4 a, const f32x4 b) { u32x4 w; w.x = cvt_pk_bf16(a[0], a[1]); w.y = cvt_pk_bf16(a[2], a[3]); w.z = cvt_pk_bf16(b[0], b[1]); w.w = cvt_pk_bf16(b[2], b[3]); return w; }
;     __device__ __forceinline__ void operator()(const f32x4 (&acc)[2][2][4][2], const pg8::Unit& u, int wr, int wc, int fr, int fq) const {
;     ...
;                 const int row = row0 + ai * 128 + m * 16, s = s0 + ai * 128 + m * 16;
;                 const float rs = 1.0f / sqrtf(SS[(size_t)row * 2 + 1] * (1.0f / 512.0f) + 1e-6f);
;                 *(u32x4*)(KN + (size_t)row * 2048 + u.pn * 128 + cw) = pack8(acc[ai][0][m][0] * rs, acc[ai][0][m][1] * rs);
;                 bf16_t* vp = VtM + (size_t)((b * 16 + u.pn) * 128 + cw) * SEQ + s;
; #pragma unroll
;                 for (int n = 0; n < 2; ++n) {
;                     const f32x4 x = acc[ai][1][m][n] * rs;
;                     const unsigned p0 = cvt_pk_bf16(x[0], x[1]), p1 = cvt_pk_bf16(x[2], x[3]);
;                     vp[(size_t)(4 * n + 0) * SEQ] = (bf16_t)(p0 & 0xffffu); vp[(size_t)(4 * n + 1) * SEQ] = (bf16_t)(p0 >> 16);
;                     vp[(size_t)(4 * n + 2) * SEQ] = (bf16_t)(p1 & 0xffffu); vp[(size_t)(4 * n + 3) * SEQ] = (bf16_t)(p1 >> 16);
;                 }
	v_mov_b32_e32 v36, v251
	v_lshlrev_b64 v[34:35], 12, v[48:49]
	v_lshl_add_u64 v[34:35], s[38:39], 0, v[34:35]
	v_lshl_add_u64 v[34:35], v[34:35], 0, s[48:49]
	v_lshl_add_u64 v[34:35], v[34:35], 0, v[136:137]
	v_add_u32_e32 v32, 0xb0, v162
	v_ashrrev_i32_e32 v33, 31, v32
	v_fmamk_f32 v36, v36, 0x3b000000, v183
	v_mul_f32_e32 v37, 0x4f800000, v36
	v_cmp_gt_f32_e32 vcc, s83, v36
	s_nop 1
	v_cndmask_b32_e32 v38, v36, v37, vcc
	v_sqrt_f32_e32 v39, v38
	v_lshl_add_u64 v[36:37], v[32:33], 3, s[16:17]
	v_add_u32_e32 v40, -1, v39
	v_add_u32_e32 v41, 1, v39
	v_fma_f32 v42, -v40, v39, v38
	v_fma_f32 v43, -v41, v39, v38
	v_cmp_ge_f32_e64 s[8:9], 0, v42
	s_nop 1
	v_cndmask_b32_e64 v39, v39, v40, s[8:9]
	v_cmp_lt_f32_e64 s[8:9], 0, v43
	s_nop 1
	v_cndmask_b32_e64 v39, v39, v41, s[8:9]
	v_mul_f32_e32 v40, 0x37800000, v39
	v_cndmask_b32_e32 v39, v39, v40, vcc
	v_cmp_class_f32_e32 vcc, v38, v184
	s_nop 1
	v_cndmask_b32_e32 v38, v39, v38, vcc
	v_div_scale_f32 v39, s[8:9], v38, v38, 1.0
	v_rcp_f32_e32 v40, v39
	v_div_scale_f32 v41, vcc, 1.0, v38, 1.0
	v_fma_f32 v42, -v39, v40, 1.0
	v_fmac_f32_e32 v40, v42, v40
	v_mul_f32_e32 v42, v41, v40
	v_fma_f32 v43, -v39, v42, v41
	v_fmac_f32_e32 v42, v43, v40
	v_fma_f32 v39, -v39, v42, v41
	v_div_fmas_f32 v39, v39, v40, v42
	v_div_fixup_f32 v38, v39, v38, 1.0
	v_pk_mul_f32 v[30:31], v[30:31], v[38:39] op_sel_hi:[1,0]
	v_pk_mul_f32 v[28:29], v[28:29], v[38:39] op_sel_hi:[1,0]
	v_pk_mul_f32 v[26:27], v[26:27], v[38:39] op_sel_hi:[1,0]
	v_pk_mul_f32 v[24:25], v[24:25], v[38:39] op_sel_hi:[1,0]
	v_pk_mul_f32 v[22:23], v[22:23], v[38:39] op_sel_hi:[1,0]
	v_pk_mul_f32 v[20:21], v[20:21], v[38:39] op_sel_hi:[1,0]
	v_pk_mul_f32 v[40:41], v[18:19], v[38:39] op_sel_hi:[1,0]
	v_pk_mul_f32 v[38:39], v[16:17], v[38:39] op_sel_hi:[1,0]
	v_cvt_pk_bf16_f32 v16, v28, v29
	v_cvt_pk_bf16_f32 v17, v30, v31
	v_cvt_pk_bf16_f32 v18, v24, v25
	v_cvt_pk_bf16_f32 v19, v26, v27
	global_store_dwordx4 v[34:35], v[16:19], off
	s_nop 1
	v_cvt_pk_bf16_f32 v16, v20, v21
	v_cvt_pk_bf16_f32 v17, v22, v23
	global_store_short v[152:153], v16, off offset:320
	global_store_short_d16_hi v[154:155], v16, off offset:320
	global_store_short v[156:157], v17, off offset:320
	global_store_short_d16_hi v[158:159], v17, off offset:320
	v_cvt_pk_bf16_f32 v16, v38, v39
	v_cvt_pk_bf16_f32 v17, v40, v41
	global_store_short v[148:149], v16, off offset:320
	global_store_short_d16_hi v[150:151], v16, off offset:320
	global_store_short v[160:161], v17, off offset:320
	global_store_short_d16_hi v[164:165], v17, off offset:320
	s_waitcnt vmcnt(63)
	v_mov_b32_e32 v16, v252
	v_fmamk_f32 v16, v16, 0x3b000000, v183
	v_mul_f32_e32 v17, 0x4f800000, v16
	v_cmp_gt_f32_e32 vcc, s83, v16
	s_nop 1
	v_cndmask_b32_e32 v18, v16, v17, vcc
	v_sqrt_f32_e32 v19, v18
	v_lshlrev_b64 v[16:17], 12, v[32:33]
	v_lshl_add_u64 v[16:17], s[38:39], 0, v[16:17]
	v_lshl_add_u64 v[16:17], v[16:17], 0, s[48:49]
	v_add_u32_e32 v20, -1, v19
	v_add_u32_e32 v21, 1, v19
	v_fma_f32 v22, -v20, v19, v18
	v_fma_f32 v23, -v21, v19, v18
	v_cmp_ge_f32_e64 s[8:9], 0, v22
	v_lshl_add_u64 v[16:17], v[16:17], 0, v[136:137]
	s_nop 0
	v_cndmask_b32_e64 v19, v19, v20, s[8:9]
	v_cmp_lt_f32_e64 s[8:9], 0, v23
	s_nop 1
	v_cndmask_b32_e64 v19, v19, v21, s[8:9]
	v_mul_f32_e32 v20, 0x37800000, v19
	v_cndmask_b32_e32 v19, v19, v20, vcc
	v_cmp_class_f32_e32 vcc, v18, v184
	s_nop 1
	v_cndmask_b32_e32 v18, v19, v18, vcc
	v_div_scale_f32 v19, s[8:9], v18, v18, 1.0
	v_rcp_f32_e32 v20, v19
	v_div_scale_f32 v21, vcc, 1.0, v18, 1.0
	v_fma_f32 v22, -v19, v20, 1.0
	v_fmac_f32_e32 v20, v22, v20
	v_mul_f32_e32 v22, v21, v20
	v_fma_f32 v23, -v19, v22, v21
	v_fmac_f32_e32 v22, v23, v20
	v_fma_f32 v19, -v19, v22, v21
	v_div_fmas_f32 v19, v19, v20, v22
	v_div_fixup_f32 v18, v19, v18, 1.0
	v_pk_mul_f32 v[14:15], v[14:15], v[18:19] op_sel_hi:[1,0]
	v_pk_mul_f32 v[12:13], v[12:13], v[18:19] op_sel_hi:[1,0]
	v_pk_mul_f32 v[10:11], v[10:11], v[18:19] op_sel_hi:[1,0]
	v_pk_mul_f32 v[8:9], v[8:9], v[18:19] op_sel_hi:[1,0]
	v_pk_mul_f32 v[6:7], v[6:7], v[18:19] op_sel_hi:[1,0]
	v_pk_mul_f32 v[4:5], v[4:5], v[18:19] op_sel_hi:[1,0]
	v_pk_mul_f32 v[20:21], v[2:3], v[18:19] op_sel_hi:[1,0]
	v_pk_mul_f32 v[18:19], v[0:1], v[18:19] op_sel_hi:[1,0]
	v_cvt_pk_bf16_f32 v0, v12, v13
	v_cvt_pk_bf16_f32 v1, v14, v15
	v_cvt_pk_bf16_f32 v2, v8, v9
	v_cvt_pk_bf16_f32 v3, v10, v11
	global_store_dwordx4 v[16:17], v[0:3], off
	s_and_b64 vcc, exec, s[6:7]
	s_mov_b64 s[6:7], -1
	v_cvt_pk_bf16_f32 v0, v4, v5
	v_cvt_pk_bf16_f32 v1, v6, v7
	global_store_short v[152:153], v0, off offset:352
	global_store_short_d16_hi v[154:155], v0, off offset:352
	global_store_short v[156:157], v1, off offset:352
	global_store_short_d16_hi v[158:159], v1, off offset:352
	v_cvt_pk_bf16_f32 v0, v18, v19
	v_cvt_pk_bf16_f32 v1, v20, v21
	global_store_short v[148:149], v0, off offset:352
	global_store_short_d16_hi v[150:151], v0, off offset:352
	global_store_short v[160:161], v1, off offset:352
	global_store_short_d16_hi v[164:165], v1, off offset:352
	s_cbranch_vccnz .LBB0_1043
	s_andn2_b64 vcc, exec, s[24:25]
	s_cbranch_vccnz .LBB0_1042
	s_barrier
	s_branch .LBB0_1042
